# CO: CN + layer-1 top-k phase idle blocks take 8 transposes tiles each instead of 4 (1920 more tiles out of P0b)
# baseline (speedup 1.0000x reference)
; __device__ __forceinline__ TrJob tr_decode(const Params& p, char* ws, int job) {
;   TrJob t;
;   int l = job / TJ_PER_LAYER, rj = job % TJ_PER_LAYER;
;   if (rj < 640) {
;     t.src = p.w_in + (size_t)l * 1024 * 2560; t.K = 1024; t.N = 2560; t.kt = rj / 40; t.nt = rj % 40;
;     t.dst = (u16*)(ws + OFF_WINT) + (size_t)l * 2560 * 1024; t.mode = 0;
;   } else if (rj < 896) {
;     rj -= 640;
;     t.src = p.w_out + (size_t)l * 1024 * 1024; t.K = 1024; t.N = 1024; t.kt = rj / 16; t.nt = rj % 16;
;     t.dst = (u16*)(ws + OFF_WOUTT) + (size_t)l * 1024 * 1024; t.mode = 0;
;   } else {
;     rj -= 896;
;     int e = rj / 1536, q = rj % 1536;
;     size_t eo = (size_t)(l * 16 + e);
;     if (q < 512) {
;       t.src = p.w_gate + eo * 1024 * 2048; t.K = 1024; t.N = 2048; t.kt = q / 32; t.nt = q % 32;
;       t.dst = (u16*)(ws + OFF_WGUT) + eo * 4096 * 1024; t.mode = 1;
;     } else if (q < 1024) {
;       q -= 512;
;       t.src = p.w_up + eo * 1024 * 2048; t.K = 1024; t.N = 2048; t.kt = q / 32; t.nt = q % 32;
;       t.dst = (u16*)(ws + OFF_WGUT) + eo * 4096 * 1024; t.mode = 2;
;     } else {
;       q -= 1024;
;       t.src = p.w_down + eo * 2048 * 1024; t.K = 2048; t.N = 1024; t.kt = q / 16; t.nt = q % 16;
;       t.dst = (u16*)(ws + OFF_WDT) + eo * 1024 * 2048; t.mode = 0;
;     }
;   }
; __device__ __forceinline__ void p0_transposes(const Params& p, char* smem, int bid, int nb, int jlo, int jhi) {
;     ...
;   for (; j < jhi; j += 2 * nb) {
;     const int jn = j + 2 * nb;
;     if (jn < jhi) { tr_load(p, ws, jn, tid, n0); tr_load(p, ws, jn + 1, tid, n1); }
.LBB0_174:
	s_add_i32 s96, s97, s75
	s_cmp_gt_i32 s96, 0x682f
	s_cselect_b64 s[0:1], -1, 0
	s_and_b64 vcc, exec, s[0:1]
	s_cbranch_vccnz .LBB0_208
	s_mul_hi_i32 s10, s96, 0x5254e78f
	s_lshr_b32 s11, s10, 31
	s_ashr_i32 s10, s10, 13
	s_add_i32 s52, s10, s11
	s_mul_i32 s10, s52, 0xffff9c80
	s_add_i32 s10, s96, s10
	s_cmpk_gt_i32 s10, 0x27f
	s_mov_b64 s[58:59], -1
	s_cbranch_scc0 .LBB0_189
	s_cmpk_gt_u32 s10, 0x37f
	s_cbranch_scc0 .LBB0_186
	s_add_i32 s11, s10, 0xfc80
	s_and_b32 s33, s11, 0xffff
	s_mul_i32 s33, s33, 0xaaab
	s_lshr_b32 s33, s33, 26
	s_mul_i32 s40, s33, 0x600
	s_sub_i32 s11, s11, s40
	s_and_b32 s40, s11, 0xffff
	s_lshl_b32 s11, s52, 4
	s_add_i32 s54, s11, s33
	s_ashr_i32 s55, s54, 31
	s_lshl_b64 s[58:59], s[54:55], 23
	s_cmpk_gt_u32 s40, 0x1ff
	s_mov_b64 s[60:61], -1
	s_cbranch_scc0 .LBB0_183
	s_cmpk_gt_u32 s40, 0x3ff
	s_mov_b64 s[56:57], -1
	s_cbranch_scc0 .LBB0_180
	v_readlane_b32 s12, v238, 25
	s_add_i32 s11, s40, 0xfffffc00
	v_readlane_b32 s18, v238, 31
	v_readlane_b32 s19, v238, 32
	s_add_u32 s54, s18, s58
	v_readlane_b32 s13, v238, 26
	v_readlane_b32 s14, v238, 27
	v_readlane_b32 s15, v238, 28
	v_readlane_b32 s16, v238, 29
	v_readlane_b32 s17, v238, 30
	s_addc_u32 s55, s19, s59
	s_lshr_b32 s33, s11, 4
	s_and_b32 s11, s40, 15
	s_mov_b64 s[56:57], 0

; #define GSYNC() do { xcd_barrier(xb); if (REP_MASK & 256) xcd_barrier(xb); } while (0)
; #define LAUNDER(v) asm volatile("" : "+s"(v))
; __device__ __forceinline__ int vtid() { int t = threadIdx.x; asm volatile("" : "+v"(t)); return t; }
; __device__ __forceinline__ void p0_transposes(const Params& p, char* smem, int bid, int nb, int jlo, int jhi) {
;   const int tid = vtid();
;   char* ws = p.ws;
;   LAUNDER(ws);
;   float* tileA = (float*)smem;
;   float* tileB = tileA + 64 * 65;
;   float4 c0[4], c1[4], n0[4], n1[4];
;   int j = jlo + bid * 2;
;   if (j < jhi) { tr_load(p, ws, j, tid, c0); tr_load(p, ws, j + 1, tid, c1); }
;   for (; j < jhi; j += 2 * nb) {
; __global__ void __launch_bounds__(256, 2) fwd_megakernel(Params p) {
;     ...
;     for (int rep = 0; rep < NREP(5); ++rep) {
;       const int nj = l == 0 ? 64 : 32;
;       for (int j = bid; j < nj; j += nb) topk_job(p, smem, j & 31, j >= 32);
;       GSYNC();
.Ltrp5_l1:
	v_readlane_b32 s100, v236, 62
	v_readlane_b32 s101, v236, 63
	v_writelane_b32 v255, s64, 0
	v_writelane_b32 v255, s65, 1
	v_writelane_b32 v255, s66, 2
	v_writelane_b32 v255, s67, 3
	v_writelane_b32 v255, s68, 4
	v_writelane_b32 v255, s69, 5
	v_writelane_b32 v255, s70, 6
	v_writelane_b32 v255, s71, 7
	v_writelane_b32 v255, s72, 8
	v_writelane_b32 v255, s73, 9
	v_writelane_b32 v255, s74, 10
	v_writelane_b32 v255, s75, 11
	v_writelane_b32 v255, s76, 12
	v_writelane_b32 v255, s77, 13
	v_writelane_b32 v255, s78, 14
	v_writelane_b32 v255, s79, 15
	v_writelane_b32 v255, s80, 16
	v_writelane_b32 v255, s81, 17
	v_writelane_b32 v255, s82, 18
	v_writelane_b32 v255, s83, 19
	v_writelane_b32 v255, s84, 20
	v_writelane_b32 v255, s85, 21
	v_writelane_b32 v255, s86, 22
	v_writelane_b32 v255, s87, 23
	v_writelane_b32 v255, s88, 24
	v_writelane_b32 v255, s89, 25
	v_writelane_b32 v255, s90, 26
	v_writelane_b32 v255, s91, 27
	v_writelane_b32 v255, s92, 28
	v_writelane_b32 v255, s93, 29
	v_writelane_b32 v255, s94, 30
	v_writelane_b32 v255, s95, 31
	v_writelane_b32 v255, s96, 32
	v_writelane_b32 v255, s97, 33
	v_writelane_b32 v255, s98, 34
	v_writelane_b32 v255, s99, 35
	v_writelane_b32 v255, vcc_lo, 36
	v_writelane_b32 v255, vcc_hi, 37
	s_load_dwordx4 s[64:67], s[100:101], 0x40
	s_load_dwordx4 s[68:71], s[100:101], 0xc8
	s_load_dwordx2 s[72:73], s[100:101], 0xd8
	s_load_dwordx2 s[74:75], s[100:101], 0xe8
	v_and_b32_e32 v241, 15, v172
	v_lshrrev_b32_e32 v242, 4, v172
	v_lshlrev_b32_e32 v241, 4, v241
	v_mul_u32_u24_e32 v243, 0x104, v242
	v_add_u32_e32 v243, v243, v241
	v_and_b32_e32 v246, 7, v172
	v_lshrrev_b32_e32 v245, 3, v172
	v_mul_u32_u24_e32 v244, 0x820, v246
	v_lshl_add_u32 v244, v245, 2, v244
	v_lshlrev_b32_e32 v246, 4, v246
	v_readlane_b32 s76, v239, 0
	s_add_u32 s76, s76, 26640
	s_movk_i32 s77, 4
	s_mov_b32 s96, 0
	s_waitcnt lgkmcnt(0)
